# P4 (EpiGrp) epilogue: first 5 SG gate quads prefetched before the tile's K loop into VGPRs free across the loop (HBM latency of the epilogue's first loads hidden behind the MFMA loop)
# speedup vs baseline: 1.0197x; 1.0023x over previous
; template <class Epi>
; __device__ __forceinline__ void gemm_phase(LAS unsigned char* lds, const Gemm g, const StaticOrder& S, const Epi& E) {
;     ...
;         for (int a = 0; a < 2; ++a)
; #pragma unroll
;             for (int b = 0; b < 2; ++b)
; #pragma unroll
;                 for (int m = 0; m < 4; ++m)
; #pragma unroll
;                     for (int n = 0; n < 2; ++n) acc[a][b][m][n] = (f32x4){0.f, 0.f, 0.f, 0.f};
;         cur = nxt; cA = nA; cB = nB; ++ui;
;     __device__ __forceinline__ void operator()(const f32x4 (&acc)[2][2][4][2], const Unit& u, int wr, int wc, int fr, int fq) const {
;     ...
;             for (int m = 0; m < 4; ++m) { const size_t off = (size_t)(row0 + ai * HALF + m * 16) * DM + col0;
; #pragma unroll
;                 for (int bj = 0; bj < 2; ++bj) { const u32x4 gw = *(const u32x4*)(SG + off + bj * HALF);
.LBB0_573:
	s_ashr_i32 s25, s24, 31
	s_lshl_b64 s[52:53], s[24:25], 18
	s_add_u32 s52, s59, s52
	s_addc_u32 s53, s67, s53
	s_and_b64 s[4:5], s[4:5], exec
	s_cselect_b32 s25, s53, s35
	s_cselect_b32 s27, s52, s34
	s_add_u32 s4, s36, 0x80080
	s_addc_u32 s5, s37, 0
	s_add_u32 s51, s34, 0x100
	v_mov_b32_e32 v0, 0
	s_addc_u32 s54, s35, 0
	s_mov_b32 s55, -2
	v_mov_b32_e32 v1, v0
	v_mov_b32_e32 v2, v0
	v_mov_b32_e32 v3, v0
	v_mov_b32_e32 v4, v0
	v_mov_b32_e32 v5, v0
	v_mov_b32_e32 v6, v0
	v_mov_b32_e32 v7, v0
	v_mov_b32_e32 v12, v0
	v_mov_b32_e32 v13, v0
	v_mov_b32_e32 v14, v0
	v_mov_b32_e32 v15, v0
	v_mov_b32_e32 v20, v0
	v_mov_b32_e32 v21, v0
	v_mov_b32_e32 v22, v0
	v_mov_b32_e32 v23, v0
	v_mov_b32_e32 v28, v0
	v_mov_b32_e32 v29, v0
	v_mov_b32_e32 v30, v0
	v_mov_b32_e32 v31, v0
	v_mov_b32_e32 v36, v0
	v_mov_b32_e32 v37, v0
	v_mov_b32_e32 v38, v0
	v_mov_b32_e32 v39, v0
	v_mov_b32_e32 v44, v0
	v_mov_b32_e32 v45, v0
	v_mov_b32_e32 v46, v0
	v_mov_b32_e32 v47, v0
	v_mov_b32_e32 v52, v0
	v_mov_b32_e32 v53, v0
	v_mov_b32_e32 v54, v0
	v_mov_b32_e32 v55, v0
	v_mov_b32_e32 v8, v0
	v_mov_b32_e32 v9, v0
	v_mov_b32_e32 v10, v0
	v_mov_b32_e32 v11, v0
	v_mov_b32_e32 v16, v0
	v_mov_b32_e32 v17, v0
	v_mov_b32_e32 v18, v0
	v_mov_b32_e32 v19, v0
	v_mov_b32_e32 v24, v0
	v_mov_b32_e32 v25, v0
	v_mov_b32_e32 v26, v0
	v_mov_b32_e32 v27, v0
	v_mov_b32_e32 v32, v0
	v_mov_b32_e32 v33, v0
	v_mov_b32_e32 v34, v0
	v_mov_b32_e32 v35, v0
	v_mov_b32_e32 v40, v0
	v_mov_b32_e32 v41, v0
	v_mov_b32_e32 v42, v0
	v_mov_b32_e32 v43, v0
	v_mov_b32_e32 v48, v0
	v_mov_b32_e32 v49, v0
	v_mov_b32_e32 v50, v0
	v_mov_b32_e32 v51, v0
	v_mov_b32_e32 v56, v0
	v_mov_b32_e32 v57, v0
	v_mov_b32_e32 v58, v0
	v_mov_b32_e32 v59, v0
	v_mov_b32_e32 v60, v0
	v_mov_b32_e32 v61, v0
	v_mov_b32_e32 v62, v0
	v_mov_b32_e32 v63, v0
	v_mov_b32_e32 v64, v0
	v_mov_b32_e32 v65, v0
	v_mov_b32_e32 v66, v0
	v_mov_b32_e32 v67, v0
	v_mov_b32_e32 v68, v0
	v_mov_b32_e32 v69, v0
	v_mov_b32_e32 v70, v0
	v_mov_b32_e32 v71, v0
	v_mov_b32_e32 v76, v0
	v_mov_b32_e32 v77, v0
	v_mov_b32_e32 v78, v0
	v_mov_b32_e32 v79, v0
	v_mov_b32_e32 v84, v0
	v_mov_b32_e32 v85, v0
	v_mov_b32_e32 v86, v0
	v_mov_b32_e32 v87, v0
	v_mov_b32_e32 v108, v0
	v_mov_b32_e32 v109, v0
	v_mov_b32_e32 v110, v0
	v_mov_b32_e32 v111, v0
	v_mov_b32_e32 v116, v0
	v_mov_b32_e32 v117, v0
	v_mov_b32_e32 v118, v0
	v_mov_b32_e32 v119, v0
	v_mov_b32_e32 v140, v0
	v_mov_b32_e32 v141, v0
	v_mov_b32_e32 v142, v0
	v_mov_b32_e32 v143, v0
	v_mov_b32_e32 v148, v0
	v_mov_b32_e32 v149, v0
	v_mov_b32_e32 v150, v0
	v_mov_b32_e32 v151, v0
	v_mov_b32_e32 v72, v0
	v_mov_b32_e32 v73, v0
	v_mov_b32_e32 v74, v0
	v_mov_b32_e32 v75, v0
	v_mov_b32_e32 v80, v0
	v_mov_b32_e32 v81, v0
	v_mov_b32_e32 v82, v0
	v_mov_b32_e32 v83, v0
	v_mov_b32_e32 v104, v0
	v_mov_b32_e32 v105, v0
	v_mov_b32_e32 v106, v0
	v_mov_b32_e32 v107, v0
	v_mov_b32_e32 v112, v0
	v_mov_b32_e32 v113, v0
	v_mov_b32_e32 v114, v0
	v_mov_b32_e32 v115, v0
	v_mov_b32_e32 v136, v0
	v_mov_b32_e32 v137, v0
	v_mov_b32_e32 v138, v0
	v_mov_b32_e32 v139, v0
	v_mov_b32_e32 v144, v0
	v_mov_b32_e32 v145, v0
	v_mov_b32_e32 v146, v0
	v_mov_b32_e32 v147, v0
	v_mov_b32_e32 v152, v0
	v_mov_b32_e32 v153, v0
	v_mov_b32_e32 v154, v0
	v_mov_b32_e32 v155, v0
	v_mov_b32_e32 v156, v0
	v_mov_b32_e32 v157, v0
	v_mov_b32_e32 v158, v0
	v_mov_b32_e32 v159, v0
	v_lshl_or_b32 v246, s50, 8, v184
	v_lshl_add_u32 v199, s30, 8, v182
	v_lshl_add_u32 v246, v199, 11, v246
	v_lshlrev_b32_e32 v246, 1, v246
	global_load_dwordx4 v[226:229], v246, s[14:15]
	global_load_dwordx4 v[230:233], v246, s[14:15] offset:256
	v_add_u32_e32 v199, 0x10000, v246
	global_load_dwordx4 v[234:237], v199, s[14:15]
	global_load_dwordx4 v[238:241], v199, s[14:15] offset:256
	v_add_u32_e32 v199, 0x20000, v246
	global_load_dwordx4 v[242:245], v199, s[14:15]

; __device__ __forceinline__ float bf_lo(unsigned w) { return __uint_as_float(w << 16); }
; __device__ __forceinline__ float bf_hi(unsigned w) { return __uint_as_float(w & 0xffff0000u); }
; __device__ __forceinline__ u32x4 pack8(f32x4 v0, f32x4 v1) { u32x4 w; w.x = cvt_pk_bf16(v0[0], v0[1]); w.y = cvt_pk_bf16(v0[2], v0[3]); w.z = cvt_pk_bf16(v1[0], v1[1]); w.w = cvt_pk_bf16(v1[2], v1[3]); return w; }
;     __device__ __forceinline__ void operator()(const f32x4 (&acc)[2][2][4][2], const Unit& u, int wr, int wc, int fr, int fq) const {
;     ...
;         f32x4 bv[2][2], sv[2][2];
; #pragma unroll
;         for (int bj = 0; bj < 2; ++bj)
; #pragma unroll
;             for (int n = 0; n < 2; ++n) { bv[bj][n] = *(const f32x4*)(bias + col0 + bj * HALF + 4 * n); sv[bj][n] = *(const f32x4*)(scale + col0 + bj * HALF + 4 * n); }
; #pragma unroll
;         for (int ai = 0; ai < 2; ++ai)
; #pragma unroll
;             for (int m = 0; m < 4; ++m) { const size_t off = (size_t)(row0 + ai * HALF + m * 16) * DM + col0;
; #pragma unroll
;                 for (int bj = 0; bj < 2; ++bj) { const u32x4 gw = *(const u32x4*)(SG + off + bj * HALF);
;                     f32x4 v0 = (acc[ai][bj][m][0] + bv[bj][0]) * sv[bj][0], v1 = (acc[ai][bj][m][1] + bv[bj][1]) * sv[bj][1];
;                     v0 = v0 * (f32x4){bf_lo(gw.x), bf_hi(gw.x), bf_lo(gw.y), bf_hi(gw.y)}; v1 = v1 * (f32x4){bf_lo(gw.z), bf_hi(gw.z), bf_lo(gw.w), bf_hi(gw.w)};
;                     *(u32x4*)(Z + off + bj * HALF) = pack8(v0, v1); } }
.LBB0_577:
	v_lshl_or_b32 v178, s50, 8, v184
	v_readlane_b32 s68, v247, 0
	v_ashrrev_i32_e32 v179, 31, v178
	v_readlane_b32 s69, v247, 1
	v_readlane_b32 s70, v247, 2
	v_readlane_b32 s71, v247, 3
	v_readlane_b32 s72, v247, 4
	v_readlane_b32 s73, v247, 5
	v_lshlrev_b64 v[88:89], 2, v[178:179]
	v_readlane_b32 s74, v247, 6
	v_readlane_b32 s75, v247, 7
	s_mov_b64 s[68:69], s[72:73]
	v_lshl_add_u32 v180, s30, 8, v182
	s_mov_b64 s[70:71], s[74:75]
	v_lshl_add_u64 v[90:91], s[68:69], 0, v[88:89]
	v_ashrrev_i32_e32 v181, 31, v180
	v_lshl_add_u64 v[96:97], s[70:71], 0, v[88:89]
	global_load_dwordx4 v[124:127], v[90:91], off offset:16
	global_load_dwordx4 v[132:135], v[90:91], off
	global_load_dwordx4 v[120:123], v[96:97], off offset:16
	global_load_dwordx4 v[128:131], v[96:97], off
	v_lshlrev_b64 v[88:89], 11, v[180:181]
	v_lshl_add_u64 v[88:89], v[88:89], 0, v[178:179]
	v_lshlrev_b64 v[176:177], 1, v[88:89]
	v_lshl_add_u64 v[192:193], s[14:15], 0, v[176:177]
	global_load_dwordx4 v[92:95], v[90:91], off offset:528
	global_load_dwordx4 v[100:103], v[90:91], off offset:512
	s_nop 0
	global_load_dwordx4 v[88:91], v[96:97], off offset:528
	s_nop 0
	global_load_dwordx4 v[96:99], v[96:97], off offset:512
	v_add_u32_e32 v199, 0x20000, v176
	global_load_dwordx4 v[200:203], v199, s[14:15] offset:256
	v_add_u32_e32 v199, 0x30000, v176
	global_load_dwordx4 v[204:207], v199, s[14:15]
	v_add_u32_e32 v199, 0x30000, v176
	global_load_dwordx4 v[208:211], v199, s[14:15] offset:256
	v_add_u32_e32 v199, 0x80000, v176
	global_load_dwordx4 v[212:215], v199, s[14:15]
	v_add_u32_e32 v199, 0x80000, v176
	global_load_dwordx4 v[216:219], v199, s[14:15] offset:256
	s_mov_b64 s[4:5], 0x80000
	v_readlane_b32 s76, v247, 8
	v_readlane_b32 s77, v247, 9
	v_readlane_b32 s78, v247, 10
	v_readlane_b32 s79, v247, 11
	v_readlane_b32 s80, v247, 12
	v_readlane_b32 s81, v247, 13
	v_readlane_b32 s82, v247, 14
	v_readlane_b32 s83, v247, 15
	v_readlane_b32 s68, v247, 34
	s_and_b64 vcc, exec, s[0:1]
	s_mov_b64 s[0:1], -1
	v_readlane_b32 s69, v247, 35
	v_readlane_b32 s70, v247, 36
	v_readlane_b32 s71, v247, 37
	v_readlane_b32 s72, v247, 38
	v_readlane_b32 s73, v247, 39
	v_readlane_b32 s74, v247, 40
	v_readlane_b32 s75, v247, 41
	v_readlane_b32 s76, v247, 42
	v_readlane_b32 s77, v247, 43
	v_readlane_b32 s78, v247, 44
	v_readlane_b32 s79, v247, 45
	v_readlane_b32 s80, v247, 46
	v_readlane_b32 s81, v247, 47
	v_readlane_b32 s82, v247, 48
	v_readlane_b32 s83, v247, 49
	s_waitcnt vmcnt(5)
	v_pk_add_f32 v[154:155], v[154:155], v[126:127]
	v_pk_add_f32 v[158:159], v[158:159], v[134:135]
	v_pk_add_f32 v[156:157], v[156:157], v[132:133]
	v_pk_add_f32 v[152:153], v[152:153], v[124:125]
	v_pk_mul_f32 v[158:159], v[130:131], v[158:159]
	v_pk_mul_f32 v[156:157], v[128:129], v[156:157]
	v_pk_mul_f32 v[154:155], v[122:123], v[154:155]
	v_pk_mul_f32 v[152:153], v[120:121], v[152:153]
	v_lshlrev_b32_e32 v194, 16, v226
	v_and_b32_e32 v195, 0xffff0000, v226
	v_lshlrev_b32_e32 v188, 16, v227
	v_and_b32_e32 v189, 0xffff0000, v227
	v_lshlrev_b32_e32 v196, 16, v228
	v_and_b32_e32 v197, 0xffff0000, v228
	v_lshlrev_b32_e32 v190, 16, v229
	v_and_b32_e32 v191, 0xffff0000, v229
	v_pk_mul_f32 v[158:159], v[158:159], v[188:189]
	v_pk_mul_f32 v[156:157], v[156:157], v[194:195]
	v_pk_mul_f32 v[188:189], v[154:155], v[190:191]
	v_pk_mul_f32 v[154:155], v[152:153], v[196:197]
	v_cvt_pk_bf16_f32 v152, v156, v157
	v_cvt_pk_bf16_f32 v153, v158, v159
	v_lshl_add_u64 v[190:191], s[18:19], 0, v[176:177]
	v_cvt_pk_bf16_f32 v154, v154, v155
	v_cvt_pk_bf16_f32 v155, v188, v189
	v_add_u32_e32 v199, 0x90000, v176
	global_load_dwordx4 v[226:229], v199, s[14:15]
	v_or_b32_e32 v188, 16, v180
	v_ashrrev_i32_e32 v189, 31, v188
	v_lshlrev_b64 v[188:189], 11, v[188:189]
	v_pk_add_f32 v[148:149], v[148:149], v[100:101]
	v_pk_add_f32 v[142:143], v[142:143], v[94:95]
	v_pk_add_f32 v[140:141], v[140:141], v[92:93]
	v_lshl_add_u64 v[188:189], v[188:189], 0, v[178:179]
	v_pk_add_f32 v[150:151], v[150:151], v[102:103]
	v_pk_mul_f32 v[148:149], v[96:97], v[148:149]
	v_pk_mul_f32 v[142:143], v[90:91], v[142:143]
	v_pk_mul_f32 v[140:141], v[88:89], v[140:141]
	global_store_dwordx4 v[190:191], v[152:155], off
	v_lshlrev_b64 v[188:189], 1, v[188:189]
	v_pk_mul_f32 v[150:151], v[98:99], v[150:151]
	v_lshl_add_u64 v[192:193], s[14:15], 0, v[188:189]
	v_pk_add_f32 v[146:147], v[146:147], v[134:135]
	v_pk_add_f32 v[138:139], v[138:139], v[126:127]
	v_pk_add_f32 v[136:137], v[136:137], v[124:125]
	v_pk_add_f32 v[144:145], v[144:145], v[132:133]
	v_pk_mul_f32 v[146:147], v[130:131], v[146:147]
	v_pk_mul_f32 v[138:139], v[122:123], v[138:139]
	v_pk_mul_f32 v[136:137], v[120:121], v[136:137]
	v_pk_mul_f32 v[144:145], v[128:129], v[144:145]
	v_pk_add_f32 v[116:117], v[116:117], v[100:101]
	v_pk_add_f32 v[110:111], v[110:111], v[94:95]
	v_pk_add_f32 v[108:109], v[108:109], v[92:93]
	v_pk_add_f32 v[118:119], v[118:119], v[102:103]
	v_pk_mul_f32 v[116:117], v[96:97], v[116:117]
	v_pk_mul_f32 v[110:111], v[90:91], v[110:111]
	v_pk_mul_f32 v[108:109], v[88:89], v[108:109]
	v_pk_mul_f32 v[118:119], v[98:99], v[118:119]
	v_pk_add_f32 v[114:115], v[114:115], v[134:135]
	v_pk_add_f32 v[106:107], v[106:107], v[126:127]
	v_pk_add_f32 v[104:105], v[104:105], v[124:125]
	v_pk_add_f32 v[112:113], v[112:113], v[132:133]
	v_pk_mul_f32 v[114:115], v[130:131], v[114:115]
	v_pk_mul_f32 v[106:107], v[122:123], v[106:107]
	v_pk_mul_f32 v[104:105], v[120:121], v[104:105]
	v_pk_mul_f32 v[112:113], v[128:129], v[112:113]
	v_pk_add_f32 v[84:85], v[84:85], v[100:101]
	v_pk_add_f32 v[78:79], v[78:79], v[94:95]
	v_pk_add_f32 v[76:77], v[76:77], v[92:93]
	v_pk_add_f32 v[86:87], v[86:87], v[102:103]
; __device__ __forceinline__ float bf_lo(unsigned w) { return __uint_as_float(w << 16); }
; __device__ __forceinline__ float bf_hi(unsigned w) { return __uint_as_float(w & 0xffff0000u); }
; __device__ __forceinline__ u32x4 pack8(f32x4 v0, f32x4 v1) { u32x4 w; w.x = cvt_pk_bf16(v0[0], v0[1]); w.y = cvt_pk_bf16(v0[2], v0[3]); w.z = cvt_pk_bf16(v1[0], v1[1]); w.w = cvt_pk_bf16(v1[2], v1[3]); return w; }
;     __device__ __forceinline__ void operator()(const f32x4 (&acc)[2][2][4][2], const Unit& u, int wr, int wc, int fr, int fq) const {
;     ...
;         for (int ai = 0; ai < 2; ++ai)
; #pragma unroll
;             for (int m = 0; m < 4; ++m) { const size_t off = (size_t)(row0 + ai * HALF + m * 16) * DM + col0;
; #pragma unroll
;                 for (int bj = 0; bj < 2; ++bj) { const u32x4 gw = *(const u32x4*)(SG + off + bj * HALF);
;                     f32x4 v0 = (acc[ai][bj][m][0] + bv[bj][0]) * sv[bj][0], v1 = (acc[ai][bj][m][1] + bv[bj][1]) * sv[bj][1];
;                     v0 = v0 * (f32x4){bf_lo(gw.x), bf_hi(gw.x), bf_lo(gw.y), bf_hi(gw.y)}; v1 = v1 * (f32x4){bf_lo(gw.z), bf_hi(gw.z), bf_lo(gw.w), bf_hi(gw.w)};
;                     *(u32x4*)(Z + off + bj * HALF) = pack8(v0, v1); } }
	v_pk_mul_f32 v[84:85], v[96:97], v[84:85]
	v_pk_mul_f32 v[78:79], v[90:91], v[78:79]
	v_pk_mul_f32 v[76:77], v[88:89], v[76:77]
	v_pk_mul_f32 v[86:87], v[98:99], v[86:87]
	v_pk_add_f32 v[82:83], v[82:83], v[134:135]
	v_pk_add_f32 v[74:75], v[74:75], v[126:127]
	v_pk_add_f32 v[72:73], v[72:73], v[124:125]
	v_pk_add_f32 v[80:81], v[80:81], v[132:133]
	v_pk_mul_f32 v[82:83], v[130:131], v[82:83]
	v_pk_mul_f32 v[74:75], v[122:123], v[74:75]
	v_pk_mul_f32 v[72:73], v[120:121], v[72:73]
	v_pk_mul_f32 v[80:81], v[128:129], v[80:81]
	v_pk_add_f32 v[68:69], v[68:69], v[100:101]
	v_pk_add_f32 v[66:67], v[66:67], v[94:95]
	v_pk_add_f32 v[64:65], v[64:65], v[92:93]
	v_pk_add_f32 v[70:71], v[70:71], v[102:103]
	v_pk_mul_f32 v[68:69], v[96:97], v[68:69]
	v_pk_mul_f32 v[66:67], v[90:91], v[66:67]
	v_pk_mul_f32 v[64:65], v[88:89], v[64:65]
	v_pk_mul_f32 v[70:71], v[98:99], v[70:71]
	v_pk_add_f32 v[62:63], v[62:63], v[134:135]
	v_pk_add_f32 v[60:61], v[60:61], v[132:133]
	v_pk_add_f32 v[58:59], v[58:59], v[126:127]
	v_pk_add_f32 v[56:57], v[56:57], v[124:125]
	v_pk_mul_f32 v[62:63], v[130:131], v[62:63]
	v_pk_mul_f32 v[60:61], v[128:129], v[60:61]
	v_pk_mul_f32 v[58:59], v[122:123], v[58:59]
	v_pk_mul_f32 v[56:57], v[120:121], v[56:57]
	v_pk_add_f32 v[52:53], v[52:53], v[100:101]
	v_pk_add_f32 v[46:47], v[46:47], v[94:95]
	v_pk_add_f32 v[44:45], v[44:45], v[92:93]
	v_pk_add_f32 v[54:55], v[54:55], v[102:103]
	v_pk_mul_f32 v[52:53], v[96:97], v[52:53]
	v_pk_mul_f32 v[46:47], v[90:91], v[46:47]
	v_pk_mul_f32 v[44:45], v[88:89], v[44:45]
	v_pk_mul_f32 v[54:55], v[98:99], v[54:55]
	v_lshlrev_b32_e32 v152, 16, v230
	v_and_b32_e32 v153, 0xffff0000, v230
	v_lshlrev_b32_e32 v154, 16, v231
	v_and_b32_e32 v155, 0xffff0000, v231
	v_lshlrev_b32_e32 v156, 16, v232
	v_and_b32_e32 v157, 0xffff0000, v232
	v_lshlrev_b32_e32 v158, 16, v233
	v_and_b32_e32 v159, 0xffff0000, v233
	v_pk_mul_f32 v[148:149], v[148:149], v[152:153]
	v_pk_mul_f32 v[152:153], v[142:143], v[158:159]
	v_pk_mul_f32 v[142:143], v[140:141], v[156:157]
	v_pk_mul_f32 v[150:151], v[150:151], v[154:155]
	v_cvt_pk_bf16_f32 v140, v148, v149
	v_pk_add_f32 v[50:51], v[50:51], v[134:135]
	v_cvt_pk_bf16_f32 v141, v150, v151
	v_cvt_pk_bf16_f32 v142, v142, v143
	v_cvt_pk_bf16_f32 v143, v152, v153
	global_store_dwordx4 v[190:191], v[140:143], off offset:256
	v_add_u32_e32 v199, 0x90000, v176
	global_load_dwordx4 v[230:233], v199, s[14:15] offset:256
	v_pk_add_f32 v[42:43], v[42:43], v[126:127]
	v_pk_add_f32 v[40:41], v[40:41], v[124:125]
	v_pk_add_f32 v[48:49], v[48:49], v[132:133]
	v_pk_mul_f32 v[50:51], v[130:131], v[50:51]
	v_pk_mul_f32 v[42:43], v[122:123], v[42:43]
	v_pk_mul_f32 v[40:41], v[120:121], v[40:41]
	v_pk_mul_f32 v[48:49], v[128:129], v[48:49]
	v_pk_add_f32 v[36:37], v[36:37], v[100:101]
	v_pk_add_f32 v[30:31], v[30:31], v[94:95]
	v_pk_add_f32 v[28:29], v[28:29], v[92:93]
	v_pk_add_f32 v[38:39], v[38:39], v[102:103]
	v_pk_mul_f32 v[36:37], v[96:97], v[36:37]
	v_pk_mul_f32 v[30:31], v[90:91], v[30:31]
	v_pk_mul_f32 v[28:29], v[88:89], v[28:29]
	v_pk_mul_f32 v[38:39], v[98:99], v[38:39]
	v_pk_add_f32 v[34:35], v[34:35], v[134:135]
	v_pk_add_f32 v[26:27], v[26:27], v[126:127]
	v_pk_add_f32 v[24:25], v[24:25], v[124:125]
	v_pk_add_f32 v[32:33], v[32:33], v[132:133]
	v_pk_mul_f32 v[34:35], v[130:131], v[34:35]
	v_pk_mul_f32 v[26:27], v[122:123], v[26:27]
	v_pk_mul_f32 v[24:25], v[120:121], v[24:25]
	v_pk_mul_f32 v[32:33], v[128:129], v[32:33]
	v_pk_add_f32 v[20:21], v[20:21], v[100:101]
	v_pk_add_f32 v[14:15], v[14:15], v[94:95]
	v_pk_add_f32 v[12:13], v[12:13], v[92:93]
	v_pk_add_f32 v[22:23], v[22:23], v[102:103]
	v_pk_mul_f32 v[20:21], v[96:97], v[20:21]
	v_pk_mul_f32 v[14:15], v[90:91], v[14:15]
	v_pk_mul_f32 v[12:13], v[88:89], v[12:13]
	v_pk_mul_f32 v[22:23], v[98:99], v[22:23]
	v_pk_add_f32 v[18:19], v[18:19], v[134:135]
	v_pk_add_f32 v[10:11], v[10:11], v[126:127]
	v_pk_add_f32 v[8:9], v[8:9], v[124:125]
	v_pk_add_f32 v[16:17], v[16:17], v[132:133]
	v_pk_mul_f32 v[18:19], v[130:131], v[18:19]
	v_pk_mul_f32 v[10:11], v[122:123], v[10:11]
	v_pk_mul_f32 v[8:9], v[120:121], v[8:9]
	v_pk_mul_f32 v[16:17], v[128:129], v[16:17]
	v_pk_add_f32 v[4:5], v[4:5], v[100:101]
	v_pk_add_f32 v[2:3], v[2:3], v[94:95]
	v_pk_add_f32 v[0:1], v[0:1], v[92:93]
	v_pk_add_f32 v[6:7], v[6:7], v[102:103]
	v_pk_mul_f32 v[4:5], v[96:97], v[4:5]
	v_pk_mul_f32 v[2:3], v[90:91], v[2:3]
	v_pk_mul_f32 v[0:1], v[88:89], v[0:1]
	v_pk_mul_f32 v[6:7], v[98:99], v[6:7]
	v_lshlrev_b32_e32 v148, 16, v234
	v_and_b32_e32 v149, 0xffff0000, v234
	v_lshlrev_b32_e32 v140, 16, v235
	v_and_b32_e32 v141, 0xffff0000, v235
	v_lshlrev_b32_e32 v150, 16, v236
	v_and_b32_e32 v151, 0xffff0000, v236
	v_lshlrev_b32_e32 v142, 16, v237
	v_and_b32_e32 v143, 0xffff0000, v237
	v_pk_mul_f32 v[140:141], v[146:147], v[140:141]
	v_pk_mul_f32 v[142:143], v[138:139], v[142:143]
	v_pk_mul_f32 v[138:139], v[136:137], v[150:151]
	v_pk_mul_f32 v[144:145], v[144:145], v[148:149]
	v_lshl_add_u64 v[146:147], s[18:19], 0, v[188:189]
	v_cvt_pk_bf16_f32 v136, v144, v145
	v_cvt_pk_bf16_f32 v137, v140, v141
	v_cvt_pk_bf16_f32 v138, v138, v139
	v_cvt_pk_bf16_f32 v139, v142, v143
	v_add_u32_e32 v199, 0xa0000, v176
	global_load_dwordx4 v[234:237], v199, s[14:15]
	v_or_b32_e32 v144, 32, v180
	v_ashrrev_i32_e32 v145, 31, v144
	v_lshlrev_b64 v[144:145], 11, v[144:145]
	v_lshl_add_u64 v[144:145], v[144:145], 0, v[178:179]
	global_store_dwordx4 v[146:147], v[136:139], off
	v_lshlrev_b64 v[144:145], 1, v[144:145]
	v_lshl_add_u64 v[148:149], s[14:15], 0, v[144:145]
	v_lshlrev_b32_e32 v136, 16, v238
	v_and_b32_e32 v137, 0xffff0000, v238
	v_lshlrev_b32_e32 v138, 16, v239
; __device__ __forceinline__ float bf_lo(unsigned w) { return __uint_as_float(w << 16); }
; __device__ __forceinline__ float bf_hi(unsigned w) { return __uint_as_float(w & 0xffff0000u); }
; __device__ __forceinline__ u32x4 pack8(f32x4 v0, f32x4 v1) { u32x4 w; w.x = cvt_pk_bf16(v0[0], v0[1]); w.y = cvt_pk_bf16(v0[2], v0[3]); w.z = cvt_pk_bf16(v1[0], v1[1]); w.w = cvt_pk_bf16(v1[2], v1[3]); return w; }
;     __device__ __forceinline__ void operator()(const f32x4 (&acc)[2][2][4][2], const Unit& u, int wr, int wc, int fr, int fq) const {
;     ...
;         for (int ai = 0; ai < 2; ++ai)
; #pragma unroll
;             for (int m = 0; m < 4; ++m) { const size_t off = (size_t)(row0 + ai * HALF + m * 16) * DM + col0;
; #pragma unroll
;                 for (int bj = 0; bj < 2; ++bj) { const u32x4 gw = *(const u32x4*)(SG + off + bj * HALF);
;                     f32x4 v0 = (acc[ai][bj][m][0] + bv[bj][0]) * sv[bj][0], v1 = (acc[ai][bj][m][1] + bv[bj][1]) * sv[bj][1];
;                     v0 = v0 * (f32x4){bf_lo(gw.x), bf_hi(gw.x), bf_lo(gw.y), bf_hi(gw.y)}; v1 = v1 * (f32x4){bf_lo(gw.z), bf_hi(gw.z), bf_lo(gw.w), bf_hi(gw.w)};
;                     *(u32x4*)(Z + off + bj * HALF) = pack8(v0, v1); } }
	v_and_b32_e32 v139, 0xffff0000, v239
	v_lshlrev_b32_e32 v140, 16, v240
	v_and_b32_e32 v141, 0xffff0000, v240
	v_lshlrev_b32_e32 v142, 16, v241
	v_and_b32_e32 v143, 0xffff0000, v241
	v_pk_mul_f32 v[116:117], v[116:117], v[136:137]
	v_pk_mul_f32 v[136:137], v[110:111], v[142:143]
	v_pk_mul_f32 v[110:111], v[108:109], v[140:141]
	v_pk_mul_f32 v[118:119], v[118:119], v[138:139]
	v_cvt_pk_bf16_f32 v108, v116, v117
	s_nop 0
	v_cvt_pk_bf16_f32 v109, v118, v119
	v_cvt_pk_bf16_f32 v110, v110, v111
	v_cvt_pk_bf16_f32 v111, v136, v137
	global_store_dwordx4 v[146:147], v[108:111], off offset:256
	v_add_u32_e32 v199, 0xa0000, v176
	global_load_dwordx4 v[238:241], v199, s[14:15] offset:256
	v_lshlrev_b32_e32 v116, 16, v242
	v_and_b32_e32 v117, 0xffff0000, v242
	v_lshlrev_b32_e32 v108, 16, v243
	v_and_b32_e32 v109, 0xffff0000, v243
	v_lshlrev_b32_e32 v118, 16, v244
	v_and_b32_e32 v119, 0xffff0000, v244
	v_lshlrev_b32_e32 v110, 16, v245
	v_and_b32_e32 v111, 0xffff0000, v245
	v_pk_mul_f32 v[108:109], v[114:115], v[108:109]
	v_pk_mul_f32 v[110:111], v[106:107], v[110:111]
	v_pk_mul_f32 v[106:107], v[104:105], v[118:119]
	v_pk_mul_f32 v[112:113], v[112:113], v[116:117]
	v_lshl_add_u64 v[114:115], s[18:19], 0, v[144:145]
	v_cvt_pk_bf16_f32 v104, v112, v113
	v_cvt_pk_bf16_f32 v105, v108, v109
	v_cvt_pk_bf16_f32 v106, v106, v107
	v_cvt_pk_bf16_f32 v107, v110, v111
	v_add_u32_e32 v199, 0xb0000, v176
	global_load_dwordx4 v[242:245], v199, s[14:15]
	v_or_b32_e32 v112, 48, v180
	v_ashrrev_i32_e32 v113, 31, v112
	v_lshlrev_b64 v[112:113], 11, v[112:113]
	v_lshl_add_u64 v[112:113], v[112:113], 0, v[178:179]
	global_store_dwordx4 v[114:115], v[104:107], off
	v_lshlrev_b64 v[112:113], 1, v[112:113]
	v_lshl_add_u64 v[116:117], s[14:15], 0, v[112:113]
	s_waitcnt vmcnt(14)
	v_lshlrev_b32_e32 v104, 16, v200
	v_and_b32_e32 v105, 0xffff0000, v200
	v_lshlrev_b32_e32 v106, 16, v201
	v_and_b32_e32 v107, 0xffff0000, v201
	v_lshlrev_b32_e32 v108, 16, v202
	v_and_b32_e32 v109, 0xffff0000, v202
	v_lshlrev_b32_e32 v110, 16, v203
	v_and_b32_e32 v111, 0xffff0000, v203
	v_pk_mul_f32 v[84:85], v[84:85], v[104:105]
	v_pk_mul_f32 v[104:105], v[78:79], v[110:111]
	v_pk_mul_f32 v[78:79], v[76:77], v[108:109]
	v_pk_mul_f32 v[86:87], v[86:87], v[106:107]
	v_cvt_pk_bf16_f32 v76, v84, v85
	s_nop 0
	v_cvt_pk_bf16_f32 v77, v86, v87
	v_cvt_pk_bf16_f32 v78, v78, v79
	v_cvt_pk_bf16_f32 v79, v104, v105
	global_store_dwordx4 v[114:115], v[76:79], off offset:256
	v_add_u32_e32 v199, 0xb0000, v176
	global_load_dwordx4 v[200:203], v199, s[14:15] offset:256
	s_waitcnt vmcnt(15)
	v_lshlrev_b32_e32 v84, 16, v204
	v_and_b32_e32 v85, 0xffff0000, v204
	v_lshlrev_b32_e32 v76, 16, v205
	v_and_b32_e32 v77, 0xffff0000, v205
	v_lshlrev_b32_e32 v86, 16, v206
	v_and_b32_e32 v87, 0xffff0000, v206
	v_lshlrev_b32_e32 v78, 16, v207
	v_and_b32_e32 v79, 0xffff0000, v207
	v_pk_mul_f32 v[76:77], v[82:83], v[76:77]
	v_pk_mul_f32 v[78:79], v[74:75], v[78:79]
	v_pk_mul_f32 v[74:75], v[72:73], v[86:87]
	v_pk_mul_f32 v[80:81], v[80:81], v[84:85]
	v_lshl_add_u64 v[82:83], s[18:19], 0, v[112:113]
	v_cvt_pk_bf16_f32 v72, v80, v81
	v_cvt_pk_bf16_f32 v73, v76, v77
	v_cvt_pk_bf16_f32 v74, v74, v75
	v_cvt_pk_bf16_f32 v75, v78, v79
	v_lshl_add_u64 v[80:81], v[176:177], 0, s[4:5]
	global_store_dwordx4 v[82:83], v[72:75], off
	v_lshl_add_u64 v[84:85], s[14:15], 0, v[80:81]
	s_mov_b64 s[4:5], 0x90000
	s_waitcnt vmcnt(15)
	v_lshlrev_b32_e32 v72, 16, v208
	v_and_b32_e32 v73, 0xffff0000, v208
	v_lshlrev_b32_e32 v74, 16, v209
	v_and_b32_e32 v75, 0xffff0000, v209
	v_lshlrev_b32_e32 v76, 16, v210
	v_and_b32_e32 v77, 0xffff0000, v210
	v_lshlrev_b32_e32 v78, 16, v211
	v_and_b32_e32 v79, 0xffff0000, v211
	v_pk_mul_f32 v[68:69], v[68:69], v[72:73]
	v_pk_mul_f32 v[72:73], v[66:67], v[78:79]
	v_pk_mul_f32 v[66:67], v[64:65], v[76:77]
	v_pk_mul_f32 v[70:71], v[70:71], v[74:75]
	v_cvt_pk_bf16_f32 v64, v68, v69
	s_nop 0
	v_cvt_pk_bf16_f32 v65, v70, v71
	v_cvt_pk_bf16_f32 v66, v66, v67
	v_cvt_pk_bf16_f32 v67, v72, v73
	global_store_dwordx4 v[82:83], v[64:67], off offset:256
	s_waitcnt vmcnt(15)
	v_lshlrev_b32_e32 v68, 16, v212
	v_and_b32_e32 v69, 0xffff0000, v212
	v_lshlrev_b32_e32 v64, 16, v213
	v_and_b32_e32 v65, 0xffff0000, v213
	v_lshlrev_b32_e32 v70, 16, v214
	v_and_b32_e32 v71, 0xffff0000, v214
	v_lshlrev_b32_e32 v66, 16, v215
	v_and_b32_e32 v67, 0xffff0000, v215
	v_pk_mul_f32 v[62:63], v[62:63], v[64:65]
	v_pk_mul_f32 v[60:61], v[60:61], v[68:69]
	v_pk_mul_f32 v[64:65], v[58:59], v[66:67]
	v_pk_mul_f32 v[58:59], v[56:57], v[70:71]
	v_cvt_pk_bf16_f32 v56, v60, v61
	v_cvt_pk_bf16_f32 v57, v62, v63
	v_lshl_add_u64 v[66:67], s[18:19], 0, v[80:81]
	v_cvt_pk_bf16_f32 v58, v58, v59
	v_cvt_pk_bf16_f32 v59, v64, v65
	v_lshl_add_u64 v[64:65], v[176:177], 0, s[4:5]
	global_store_dwordx4 v[66:67], v[56:59], off
	v_lshl_add_u64 v[68:69], s[14:15], 0, v[64:65]
	s_mov_b64 s[4:5], 0xa0000
	s_waitcnt vmcnt(15)
; __device__ __forceinline__ float bf_lo(unsigned w) { return __uint_as_float(w << 16); }
; __device__ __forceinline__ float bf_hi(unsigned w) { return __uint_as_float(w & 0xffff0000u); }
; __device__ __forceinline__ u32x4 pack8(f32x4 v0, f32x4 v1) { u32x4 w; w.x = cvt_pk_bf16(v0[0], v0[1]); w.y = cvt_pk_bf16(v0[2], v0[3]); w.z = cvt_pk_bf16(v1[0], v1[1]); w.w = cvt_pk_bf16(v1[2], v1[3]); return w; }
;     __device__ __forceinline__ void operator()(const f32x4 (&acc)[2][2][4][2], const Unit& u, int wr, int wc, int fr, int fq) const {
;     ...
;         for (int ai = 0; ai < 2; ++ai)
; #pragma unroll
;             for (int m = 0; m < 4; ++m) { const size_t off = (size_t)(row0 + ai * HALF + m * 16) * DM + col0;
; #pragma unroll
;                 for (int bj = 0; bj < 2; ++bj) { const u32x4 gw = *(const u32x4*)(SG + off + bj * HALF);
;                     f32x4 v0 = (acc[ai][bj][m][0] + bv[bj][0]) * sv[bj][0], v1 = (acc[ai][bj][m][1] + bv[bj][1]) * sv[bj][1];
;                     v0 = v0 * (f32x4){bf_lo(gw.x), bf_hi(gw.x), bf_lo(gw.y), bf_hi(gw.y)}; v1 = v1 * (f32x4){bf_lo(gw.z), bf_hi(gw.z), bf_lo(gw.w), bf_hi(gw.w)};
;                     *(u32x4*)(Z + off + bj * HALF) = pack8(v0, v1); } }
	v_lshlrev_b32_e32 v56, 16, v216
	v_and_b32_e32 v57, 0xffff0000, v216
	v_lshlrev_b32_e32 v58, 16, v217
	v_and_b32_e32 v59, 0xffff0000, v217
	v_lshlrev_b32_e32 v60, 16, v218
	v_and_b32_e32 v61, 0xffff0000, v218
	v_lshlrev_b32_e32 v62, 16, v219
	v_and_b32_e32 v63, 0xffff0000, v219
	v_pk_mul_f32 v[52:53], v[52:53], v[56:57]
	v_pk_mul_f32 v[56:57], v[46:47], v[62:63]
	v_pk_mul_f32 v[46:47], v[44:45], v[60:61]
	v_pk_mul_f32 v[54:55], v[54:55], v[58:59]
	v_cvt_pk_bf16_f32 v44, v52, v53
	s_nop 0
	v_cvt_pk_bf16_f32 v45, v54, v55
	v_cvt_pk_bf16_f32 v46, v46, v47
	v_cvt_pk_bf16_f32 v47, v56, v57
	global_store_dwordx4 v[66:67], v[44:47], off offset:256
	s_waitcnt vmcnt(15)
	v_lshlrev_b32_e32 v52, 16, v226
	v_and_b32_e32 v53, 0xffff0000, v226
	v_lshlrev_b32_e32 v44, 16, v227
	v_and_b32_e32 v45, 0xffff0000, v227
	v_lshlrev_b32_e32 v54, 16, v228
	v_and_b32_e32 v55, 0xffff0000, v228
	v_lshlrev_b32_e32 v46, 16, v229
	v_and_b32_e32 v47, 0xffff0000, v229
	v_pk_mul_f32 v[44:45], v[50:51], v[44:45]
	v_pk_mul_f32 v[46:47], v[42:43], v[46:47]
	v_pk_mul_f32 v[42:43], v[40:41], v[54:55]
	v_pk_mul_f32 v[48:49], v[48:49], v[52:53]
	v_lshl_add_u64 v[50:51], s[18:19], 0, v[64:65]
	v_cvt_pk_bf16_f32 v40, v48, v49
	v_cvt_pk_bf16_f32 v41, v44, v45
	v_cvt_pk_bf16_f32 v42, v42, v43
	v_cvt_pk_bf16_f32 v43, v46, v47
	v_lshl_add_u64 v[48:49], v[176:177], 0, s[4:5]
	global_store_dwordx4 v[50:51], v[40:43], off
	v_lshl_add_u64 v[52:53], s[14:15], 0, v[48:49]
	s_mov_b64 s[4:5], 0xb0000
	s_waitcnt vmcnt(13)
	v_lshlrev_b32_e32 v40, 16, v230
	v_and_b32_e32 v41, 0xffff0000, v230
	v_lshlrev_b32_e32 v42, 16, v231
	v_and_b32_e32 v43, 0xffff0000, v231
	v_lshlrev_b32_e32 v44, 16, v232
	v_and_b32_e32 v45, 0xffff0000, v232
	v_lshlrev_b32_e32 v46, 16, v233
	v_and_b32_e32 v47, 0xffff0000, v233
	v_pk_mul_f32 v[36:37], v[36:37], v[40:41]
	v_pk_mul_f32 v[40:41], v[30:31], v[46:47]
	v_pk_mul_f32 v[30:31], v[28:29], v[44:45]
	v_pk_mul_f32 v[38:39], v[38:39], v[42:43]
	v_cvt_pk_bf16_f32 v28, v36, v37
	s_nop 0
	v_cvt_pk_bf16_f32 v29, v38, v39
	v_cvt_pk_bf16_f32 v30, v30, v31
	v_cvt_pk_bf16_f32 v31, v40, v41
	global_store_dwordx4 v[50:51], v[28:31], off offset:256
	s_waitcnt vmcnt(13)
	v_lshlrev_b32_e32 v36, 16, v234
	v_and_b32_e32 v37, 0xffff0000, v234
	v_lshlrev_b32_e32 v28, 16, v235
	v_and_b32_e32 v29, 0xffff0000, v235
	v_lshlrev_b32_e32 v38, 16, v236
	v_and_b32_e32 v39, 0xffff0000, v236
	v_lshlrev_b32_e32 v30, 16, v237
	v_and_b32_e32 v31, 0xffff0000, v237
	v_pk_mul_f32 v[28:29], v[34:35], v[28:29]
	v_pk_mul_f32 v[30:31], v[26:27], v[30:31]
	v_pk_mul_f32 v[26:27], v[24:25], v[38:39]
	v_pk_mul_f32 v[32:33], v[32:33], v[36:37]
	v_lshl_add_u64 v[34:35], s[18:19], 0, v[48:49]
	v_cvt_pk_bf16_f32 v24, v32, v33
	v_cvt_pk_bf16_f32 v25, v28, v29
	v_cvt_pk_bf16_f32 v26, v26, v27
	v_cvt_pk_bf16_f32 v27, v30, v31
	v_lshl_add_u64 v[32:33], v[176:177], 0, s[4:5]
	global_store_dwordx4 v[34:35], v[24:27], off
	v_lshl_add_u64 v[36:37], s[14:15], 0, v[32:33]
	s_waitcnt vmcnt(11)
	v_lshlrev_b32_e32 v24, 16, v238
	v_and_b32_e32 v25, 0xffff0000, v238
	v_lshlrev_b32_e32 v26, 16, v239
	v_and_b32_e32 v27, 0xffff0000, v239
	v_lshlrev_b32_e32 v28, 16, v240
	v_and_b32_e32 v29, 0xffff0000, v240
	v_lshlrev_b32_e32 v30, 16, v241
	v_and_b32_e32 v31, 0xffff0000, v241
	v_pk_mul_f32 v[20:21], v[20:21], v[24:25]
	v_pk_mul_f32 v[24:25], v[14:15], v[30:31]
	v_pk_mul_f32 v[14:15], v[12:13], v[28:29]
	v_pk_mul_f32 v[22:23], v[22:23], v[26:27]
	v_cvt_pk_bf16_f32 v12, v20, v21
	s_nop 0
	v_cvt_pk_bf16_f32 v13, v22, v23
	v_cvt_pk_bf16_f32 v14, v14, v15
	v_cvt_pk_bf16_f32 v15, v24, v25
	global_store_dwordx4 v[34:35], v[12:15], off offset:256
	s_waitcnt vmcnt(11)
	v_lshlrev_b32_e32 v20, 16, v242
	v_and_b32_e32 v21, 0xffff0000, v242
	v_lshlrev_b32_e32 v12, 16, v243
	v_and_b32_e32 v13, 0xffff0000, v243
	v_lshlrev_b32_e32 v22, 16, v244
	v_and_b32_e32 v23, 0xffff0000, v244
	v_lshlrev_b32_e32 v14, 16, v245
	v_and_b32_e32 v15, 0xffff0000, v245
	v_pk_mul_f32 v[12:13], v[18:19], v[12:13]
	v_pk_mul_f32 v[14:15], v[10:11], v[14:15]
	v_pk_mul_f32 v[10:11], v[8:9], v[22:23]
	v_pk_mul_f32 v[16:17], v[16:17], v[20:21]
	s_nop 0
	v_cvt_pk_bf16_f32 v8, v16, v17
	v_cvt_pk_bf16_f32 v9, v12, v13
	v_cvt_pk_bf16_f32 v10, v10, v11
	v_cvt_pk_bf16_f32 v11, v14, v15
	v_lshl_add_u64 v[16:17], s[18:19], 0, v[32:33]
	global_store_dwordx4 v[16:17], v[8:11], off
	s_waitcnt vmcnt(9)
	s_nop 0
	v_lshlrev_b32_e32 v8, 16, v200
	v_and_b32_e32 v9, 0xffff0000, v200
	v_lshlrev_b32_e32 v10, 16, v201
	v_and_b32_e32 v11, 0xffff0000, v201
	v_lshlrev_b32_e32 v12, 16, v202
	v_and_b32_e32 v13, 0xffff0000, v202
	v_lshlrev_b32_e32 v14, 16, v203
	v_and_b32_e32 v15, 0xffff0000, v203
	v_pk_mul_f32 v[4:5], v[4:5], v[8:9]
	v_pk_mul_f32 v[8:9], v[2:3], v[14:15]
	v_pk_mul_f32 v[2:3], v[0:1], v[12:13]
	v_pk_mul_f32 v[6:7], v[6:7], v[10:11]
	v_cvt_pk_bf16_f32 v0, v4, v5
	s_nop 0
	v_cvt_pk_bf16_f32 v1, v6, v7
	v_cvt_pk_bf16_f32 v2, v2, v3
	v_cvt_pk_bf16_f32 v3, v8, v9
	global_store_dwordx4 v[16:17], v[0:3], off offset:256
	s_cbranch_vccnz .LBB0_568
	s_andn2_b64 vcc, exec, s[10:11]
	s_cbranch_vccnz .LBB0_567
	s_barrier
	s_branch .LBB0_567
